# stacks MLA QK fragment-read hoisting with raw-score row-max on the K-loop rebalanced version
# baseline (speedup 1.0000x reference)
; DEV f32x4 mfma16(bf16x8 a, bf16x8 b, f32x4 c) { return __builtin_amdgcn_mfma_f32_16x16x32_bf16(a, b, c, 0, 0, 0); }
; template <int KS>
; DEV void attn_chunk(const unsigned char* Kl, const unsigned char* Vl, const bf16x8 (&qf)[2][KS], f32x4 (&O)[2][4], float (&mrun)[2], float (&lrun)[2],
;                     bool masked, int key0, int qw0, float sl2, int lane, int fr, int fq) {
;     ...
; #pragma unroll
;   for (int kt = 0; kt < 4; ++kt) {
;     sc[0][kt] = (f32x4){0.f, 0.f, 0.f, 0.f}; sc[1][kt] = (f32x4){0.f, 0.f, 0.f, 0.f};
; #pragma unroll
;     for (int kk = 0; kk < KS; ++kk) {
;       bf16x8 kf = *reinterpret_cast<const bf16x8*>(Kl + ((kt * 16 + fr) * KP + kk * 32 + fq * 8) * 2);
;       sc[0][kt] = mfma16(kf, qf[0][kk], sc[0][kt]); sc[1][kt] = mfma16(kf, qf[1][kk], sc[1][kt]);
;     }
;   }
;   bf16x8 pf[2][2];
; #pragma unroll
;   for (int qi = 0; qi < 2; ++qi) {
;     float mx = -1e30f;
; #pragma unroll
;     for (int kt = 0; kt < 4; ++kt)
; #pragma unroll
;       for (int r = 0; r < 4; ++r) { float v = sc[qi][kt][r] * sl2;
;         if (masked) { int kp = key0 + kt * 16 + fq * 4 + r; int dq = qw0 + qi * 16 + fr - kp; if (dq > 128 || dq < -128) v = -1e30f; }
;         sc[qi][kt][r] = v; mx = fmaxf(mx, v); }
;     mx = max_x16_x32(mx);
;     const float mnew = fmaxf(mrun[qi], mx);
;     const float alpha = __builtin_amdgcn_exp2f(mrun[qi] - mnew);
;     mrun[qi] = mnew;
;     float ps = 0.f;
; #pragma unroll
;     for (int kt = 0; kt < 4; ++kt)
; #pragma unroll
;       for (int r = 0; r < 4; ++r) { float pvv = __builtin_amdgcn_exp2f(sc[qi][kt][r] - mnew); ps += pvv; sc[qi][kt][r] = pvv; }
;     pf[qi][0] = pack8(sc[qi][0][0], sc[qi][0][1], sc[qi][0][2], sc[qi][0][3], sc[qi][1][0], sc[qi][1][1], sc[qi][1][2], sc[qi][1][3]);
;     pf[qi][1] = pack8(sc[qi][2][0], sc[qi][2][1], sc[qi][2][2], sc[qi][2][3], sc[qi][3][0], sc[qi][3][1], sc[qi][3][2], sc[qi][3][3]);
;     lrun[qi] = lrun[qi] * alpha + ps;
; #pragma unroll
;     for (int dt = 0; dt < 4; ++dt) O[qi][dt] *= alpha;
;   }
.LBB0_616:
	ds_read_b128 v[82:85], v202
	ds_read_b128 v[90:93], v202 offset:64
	ds_read_b128 v[222:225], v202 offset:128
	ds_read_b128 v[226:229], v202 offset:3328
	ds_read_b128 v[98:101], v202 offset:3392
	ds_read_b128 v[230:233], v202 offset:3456
	ds_read_b128 v[234:237], v202 offset:6656
	ds_read_b128 v[102:105], v202 offset:6720
	ds_read_b128 v[238:241], v202 offset:6784
	ds_read_b128 v[242:245], v202 offset:9984
	ds_read_b128 v[122:125], v202 offset:10048
	ds_read_b128 v[246:249], v202 offset:10112
	s_mov_b32 s0, 0xf149f2ca
	s_mov_b32 s1, 0x3e16c740
	s_waitcnt lgkmcnt(11)
	v_mfma_f32_16x16x32_bf16 v[86:89], v[82:85], v[2:5], 0
	v_mfma_f32_16x16x32_bf16 v[82:85], v[82:85], v[18:21], 0
	s_waitcnt lgkmcnt(10)
	v_mfma_f32_16x16x32_bf16 v[86:89], v[90:93], v[6:9], v[86:89]
	v_mfma_f32_16x16x32_bf16 v[82:85], v[90:93], v[14:17], v[82:85]
	s_waitcnt lgkmcnt(9)
	v_mfma_f32_16x16x32_bf16 v[86:89], v[222:225], v[10:13], v[86:89]
	v_mfma_f32_16x16x32_bf16 v[90:93], v[222:225], v[22:25], v[82:85]
	s_waitcnt lgkmcnt(8)
	v_mfma_f32_16x16x32_bf16 v[94:97], v[226:229], v[2:5], 0
	v_mfma_f32_16x16x32_bf16 v[82:85], v[226:229], v[18:21], 0
	s_waitcnt lgkmcnt(7)
	v_mfma_f32_16x16x32_bf16 v[94:97], v[98:101], v[6:9], v[94:97]
	v_mfma_f32_16x16x32_bf16 v[82:85], v[98:101], v[14:17], v[82:85]
	s_waitcnt lgkmcnt(6)
	v_mfma_f32_16x16x32_bf16 v[132:135], v[230:233], v[10:13], v[94:97]
	v_mfma_f32_16x16x32_bf16 v[94:97], v[230:233], v[22:25], v[82:85]
	s_waitcnt lgkmcnt(5)
	v_mfma_f32_16x16x32_bf16 v[98:101], v[234:237], v[2:5], 0
	v_mfma_f32_16x16x32_bf16 v[82:85], v[234:237], v[18:21], 0
	s_waitcnt lgkmcnt(4)
	v_mfma_f32_16x16x32_bf16 v[98:101], v[102:105], v[6:9], v[98:101]
	v_mfma_f32_16x16x32_bf16 v[82:85], v[102:105], v[14:17], v[82:85]
	s_waitcnt lgkmcnt(3)
	v_mfma_f32_16x16x32_bf16 v[140:143], v[238:241], v[10:13], v[98:101]
	v_mfma_f32_16x16x32_bf16 v[98:101], v[238:241], v[22:25], v[82:85]
	s_waitcnt lgkmcnt(2)
	v_mfma_f32_16x16x32_bf16 v[102:105], v[242:245], v[2:5], 0
	v_mfma_f32_16x16x32_bf16 v[82:85], v[242:245], v[18:21], 0
	s_waitcnt lgkmcnt(1)
	v_mfma_f32_16x16x32_bf16 v[102:105], v[122:125], v[6:9], v[102:105]
	v_mfma_f32_16x16x32_bf16 v[82:85], v[122:125], v[14:17], v[82:85]
	s_waitcnt lgkmcnt(0)
	v_mfma_f32_16x16x32_bf16 v[148:151], v[246:249], v[10:13], v[102:105]
	v_mfma_f32_16x16x32_bf16 v[102:105], v[246:249], v[22:25], v[82:85]
	v_max3_f32 v123, v90, s0, v91
	s_nop 0
	s_nop 6
	v_max3_f32 v82, v86, s0, v87
	v_max3_f32 v82, v82, v88, v89
	v_max3_f32 v82, v82, v132, v133
	v_max3_f32 v82, v82, v134, v135
	v_max3_f32 v82, v82, v140, v141
	v_max3_f32 v82, v82, v142, v143
	v_max3_f32 v82, v82, v148, v149
	v_max3_f32 v82, v82, v150, v151
	v_mul_f32_e32 v82, 0x3e16c740, v82
	v_mov_b32_e32 v83, v82
	v_max3_f32 v123, v123, v92, v93
	s_nop 0
	v_permlane32_swap_b32_e32 v82, v83
	v_max3_f32 v123, v123, v94, v95
	v_max_f32_e32 v83, v83, v83
	v_max_f32_e32 v82, v82, v82
	v_max3_f32 v123, v123, v96, v97
	v_max_f32_e32 v82, v82, v83
	v_max3_f32 v123, v123, v98, v99
	v_mov_b32_e32 v83, v82
	v_max3_f32 v123, v123, v100, v101
	s_nop 0
	v_permlane16_swap_b32_e32 v82, v83
	v_max3_f32 v123, v123, v102, v103
	v_max3_f32 v156, v218, v82, v83
	v_max3_f32 v123, v123, v104, v105
	v_fma_f32 v83, v86, s1, -v156
	v_mul_f32_e32 v123, 0x3e16c740, v123
	v_mov_b32_e32 v125, v123
	v_exp_f32_e32 v122, v83
	v_fma_f32 v83, v87, s1, -v156
	v_permlane32_swap_b32_e32 v123, v125
	v_exp_f32_e32 v126, v83
	v_fma_f32 v83, v88, s1, -v156
	v_max_f32_e32 v125, v125, v125
	v_max_f32_e32 v123, v123, v123
	v_exp_f32_e32 v124, v83
	v_fma_f32 v83, v89, s1, -v156
	v_max_f32_e32 v123, v123, v125
	v_exp_f32_e32 v128, v83
	v_fma_f32 v83, v132, s1, -v156
	v_mov_b32_e32 v125, v123
	v_exp_f32_e32 v132, v83
	v_fma_f32 v83, v133, s1, -v156
	v_permlane16_swap_b32_e32 v123, v125
	v_exp_f32_e32 v130, v83
	v_fma_f32 v83, v134, s1, -v156
	v_max3_f32 v157, v219, v123, v125
	v_exp_f32_e32 v134, v83
	v_fma_f32 v83, v135, s1, -v156
	v_fma_f32 v90, v90, s1, -v157
	v_exp_f32_e32 v138, v83
	v_fma_f32 v83, v140, s1, -v156
	v_exp_f32_e32 v123, v90
	v_fma_f32 v90, v91, s1, -v157
	v_sub_f32_e32 v82, v218, v156
	v_exp_f32_e32 v136, v83
	v_fma_f32 v83, v141, s1, -v156
	v_exp_f32_e32 v127, v90
	v_fma_f32 v90, v92, s1, -v157
	v_exp_f32_e32 v140, v83
	v_fma_f32 v83, v142, s1, -v156
	v_exp_f32_e32 v142, v82
	v_exp_f32_e32 v125, v90
	v_fma_f32 v90, v93, s1, -v157
	v_exp_f32_e32 v129, v90
	v_fma_f32 v90, v94, s1, -v157
	v_exp_f32_e32 v133, v90
	v_fma_f32 v90, v95, s1, -v157
	v_exp_f32_e32 v131, v90
	v_fma_f32 v90, v96, s1, -v157
	v_exp_f32_e32 v146, v83
	v_fma_f32 v83, v143, s1, -v156
	v_pk_mul_f32 v[68:69], v[68:69], v[142:143] op_sel_hi:[1,0]
	v_pk_mul_f32 v[66:67], v[66:67], v[142:143] op_sel_hi:[1,0]
	v_pk_mul_f32 v[72:73], v[72:73], v[142:143] op_sel_hi:[1,0]
	v_pk_mul_f32 v[70:71], v[70:71], v[142:143] op_sel_hi:[1,0]
	v_pk_mul_f32 v[76:77], v[76:77], v[142:143] op_sel_hi:[1,0]
	v_pk_mul_f32 v[74:75], v[74:75], v[142:143] op_sel_hi:[1,0]
	v_pk_mul_f32 v[80:81], v[80:81], v[142:143] op_sel_hi:[1,0]
	v_pk_mul_f32 v[78:79], v[78:79], v[142:143] op_sel_hi:[1,0]
	v_sub_f32_e32 v143, v219, v157
	v_exp_f32_e32 v135, v90
	v_fma_f32 v90, v97, s1, -v157
	v_exp_f32_e32 v139, v90
	v_fma_f32 v90, v98, s1, -v157
	v_exp_f32_e32 v143, v143
	v_exp_f32_e32 v137, v90
	v_fma_f32 v90, v99, s1, -v157
	v_exp_f32_e32 v141, v90
	v_fma_f32 v90, v100, s1, -v157
	v_exp_f32_e32 v147, v90
	v_fma_f32 v90, v101, s1, -v157
	v_exp_f32_e32 v145, v90
	v_fma_f32 v90, v102, s1, -v157
	v_mov_b32_e32 v98, v143
	v_add_u32_e32 v102, 0x6800, v203
	v_pk_mul_f32 v[52:53], v[52:53], v[98:99] op_sel_hi:[1,0]
	v_pk_mul_f32 v[50:51], v[50:51], v[98:99] op_sel_hi:[1,0]
	v_pk_mul_f32 v[56:57], v[56:57], v[98:99] op_sel_hi:[1,0]
	v_pk_mul_f32 v[54:55], v[54:55], v[98:99] op_sel_hi:[1,0]
	v_pk_mul_f32 v[60:61], v[60:61], v[98:99] op_sel_hi:[1,0]
	v_pk_mul_f32 v[58:59], v[58:59], v[98:99] op_sel_hi:[1,0]
	v_pk_mul_f32 v[64:65], v[64:65], v[98:99] op_sel_hi:[1,0]
	v_pk_mul_f32 v[62:63], v[62:63], v[98:99] op_sel_hi:[1,0]
	ds_read2_b64 v[98:101], v102 offset1:4
	v_cvt_pk_bf16_f32 v86, v122, v126
	v_cvt_pk_bf16_f32 v87, v124, v128
	v_cvt_pk_bf16_f32 v88, v132, v130
	v_cvt_pk_bf16_f32 v89, v134, v138
	v_cvt_pk_bf16_f32 v94, v123, v127
	v_cvt_pk_bf16_f32 v95, v125, v129
	v_cvt_pk_bf16_f32 v96, v133, v131
	v_cvt_pk_bf16_f32 v97, v135, v139
	v_exp_f32_e32 v144, v83
	v_fma_f32 v83, v148, s1, -v156
	s_waitcnt lgkmcnt(0)
; DEV f32x4 mfma16(bf16x8 a, bf16x8 b, f32x4 c) { return __builtin_amdgcn_mfma_f32_16x16x32_bf16(a, b, c, 0, 0, 0); }
; template <int KS>
; DEV void attn_chunk(const unsigned char* Kl, const unsigned char* Vl, const bf16x8 (&qf)[2][KS], f32x4 (&O)[2][4], float (&mrun)[2], float (&lrun)[2],
;                     bool masked, int key0, int qw0, float sl2, int lane, int fr, int fq) {
;     ...
; #pragma unroll
;   for (int dt = 0; dt < 4; ++dt)
; #pragma unroll
;     for (int sub = 0; sub < 2; ++sub) {
;       const unsigned char* vp = Vl + ((dt * 16 + fr) * VP + sub * 32 + fq * 4) * 2;
;       u32x2 v0 = *reinterpret_cast<const u32x2*>(vp), v1 = *reinterpret_cast<const u32x2*>(vp + 32);
;       u32x4 vv = {v0[0], v0[1], v1[0], v1[1]};
;       bf16x8 vf = *reinterpret_cast<bf16x8*>(&vv);
;       O[0][dt] = mfma16(vf, pf[0][sub], O[0][dt]); O[1][dt] = mfma16(vf, pf[1][sub], O[1][dt]);
;     }
	v_mfma_f32_16x16x32_bf16 v[66:69], v[98:101], v[86:89], v[66:69]
	v_exp_f32_e32 v154, v83
	v_fma_f32 v83, v149, s1, -v156
	v_exp_f32_e32 v155, v90
	v_mfma_f32_16x16x32_bf16 v[50:53], v[98:101], v[94:97], v[50:53]
	ds_read2_b64 v[98:101], v102 offset0:8 offset1:12
	v_fma_f32 v90, v103, s1, -v157
	v_exp_f32_e32 v152, v83
	v_fma_f32 v83, v150, s1, -v156
	v_exp_f32_e32 v153, v90
	v_fma_f32 v90, v104, s1, -v157
	v_exp_f32_e32 v150, v83
	v_fma_f32 v83, v151, s1, -v156
	v_exp_f32_e32 v151, v90
	v_fma_f32 v90, v105, s1, -v157
	v_exp_f32_e32 v148, v83
	v_exp_f32_e32 v149, v90
	v_cvt_pk_bf16_f32 v82, v136, v140
	v_cvt_pk_bf16_f32 v83, v146, v144
	v_cvt_pk_bf16_f32 v84, v154, v152
	v_cvt_pk_bf16_f32 v85, v150, v148
	v_cvt_pk_bf16_f32 v90, v137, v141
	v_cvt_pk_bf16_f32 v91, v147, v145
	v_cvt_pk_bf16_f32 v92, v155, v153
	v_cvt_pk_bf16_f32 v93, v151, v149
	v_add_u32_e32 v102, 0x7000, v203
	s_waitcnt lgkmcnt(0)
	v_mfma_f32_16x16x32_bf16 v[66:69], v[98:101], v[82:85], v[66:69]
	v_mfma_f32_16x16x32_bf16 v[50:53], v[98:101], v[90:93], v[50:53]
	ds_read2_b64 v[98:101], v102 offset0:32 offset1:36
	s_waitcnt lgkmcnt(0)
	v_mfma_f32_16x16x32_bf16 v[70:73], v[98:101], v[86:89], v[70:73]
	v_mfma_f32_16x16x32_bf16 v[54:57], v[98:101], v[94:97], v[54:57]
	ds_read2_b64 v[98:101], v102 offset0:40 offset1:44
	v_add_u32_e32 v102, 0x7800, v203
	s_waitcnt lgkmcnt(0)
	v_mfma_f32_16x16x32_bf16 v[70:73], v[98:101], v[82:85], v[70:73]
	v_mfma_f32_16x16x32_bf16 v[54:57], v[98:101], v[90:93], v[54:57]
	ds_read2_b64 v[98:101], v102 offset0:64 offset1:68
	s_waitcnt lgkmcnt(0)
	v_mfma_f32_16x16x32_bf16 v[74:77], v[98:101], v[86:89], v[74:77]
	v_mfma_f32_16x16x32_bf16 v[58:61], v[98:101], v[94:97], v[58:61]
	ds_read2_b64 v[98:101], v102 offset0:72 offset1:76
	v_add_u32_e32 v102, 0x8000, v203
	s_waitcnt lgkmcnt(0)
	v_mfma_f32_16x16x32_bf16 v[74:77], v[98:101], v[82:85], v[74:77]
	v_mfma_f32_16x16x32_bf16 v[58:61], v[98:101], v[90:93], v[58:61]
	ds_read2_b64 v[98:101], v102 offset0:96 offset1:100
	s_waitcnt lgkmcnt(0)
	v_mfma_f32_16x16x32_bf16 v[62:65], v[98:101], v[94:97], v[62:65]
	ds_read2_b64 v[94:97], v102 offset0:104 offset1:108
	s_waitcnt vmcnt(1)
	ds_write_b128 v199, v[38:41] offset:13312
	v_mfma_f32_16x16x32_bf16 v[78:81], v[98:101], v[86:89], v[78:81]
	s_waitcnt lgkmcnt(1)
	v_mfma_f32_16x16x32_bf16 v[86:89], v[94:97], v[82:85], v[78:81]
	v_mfma_f32_16x16x32_bf16 v[62:65], v[94:97], v[90:93], v[62:65]
	s_and_saveexec_b64 s[0:1], s[40:41]
	ds_write_b128 v200, v[42:45] offset:13312
	s_or_b64 exec, exec, s[0:1]
	s_waitcnt vmcnt(0)
	ds_write_b128 v201, v[46:49] offset:35840
	s_waitcnt lgkmcnt(0)
	s_barrier
	v_cndmask_b32_e64 v78, 0, 1, s[52:53]
	v_cmp_ne_u32_e64 s[0:1], 1, v78
	s_andn2_b64 vcc, exec, s[52:53]
	s_cbranch_vccnz .LBB0_622
	global_load_dwordx4 v[38:41], v[116:117], off
	s_and_saveexec_b64 s[48:49], s[40:41]
	s_cbranch_execz .LBB0_621
	global_load_dwordx4 v[42:45], v[118:119], off

; DEV f32x4 mfma16(bf16x8 a, bf16x8 b, f32x4 c) { return __builtin_amdgcn_mfma_f32_16x16x32_bf16(a, b, c, 0, 0, 0); }
; template <int KS>
; DEV void attn_chunk(const unsigned char* Kl, const unsigned char* Vl, const bf16x8 (&qf)[2][KS], f32x4 (&O)[2][4], float (&mrun)[2], float (&lrun)[2],
;                     bool masked, int key0, int qw0, float sl2, int lane, int fr, int fq) {
;     ...
; #pragma unroll
;   for (int kt = 0; kt < 4; ++kt) {
;     sc[0][kt] = (f32x4){0.f, 0.f, 0.f, 0.f}; sc[1][kt] = (f32x4){0.f, 0.f, 0.f, 0.f};
; #pragma unroll
;     for (int kk = 0; kk < KS; ++kk) {
;       bf16x8 kf = *reinterpret_cast<const bf16x8*>(Kl + ((kt * 16 + fr) * KP + kk * 32 + fq * 8) * 2);
;       sc[0][kt] = mfma16(kf, qf[0][kk], sc[0][kt]); sc[1][kt] = mfma16(kf, qf[1][kk], sc[1][kt]);
;     }
;   }
;   bf16x8 pf[2][2];
; #pragma unroll
;   for (int qi = 0; qi < 2; ++qi) {
;     float mx = -1e30f;
; #pragma unroll
;     for (int kt = 0; kt < 4; ++kt)
; #pragma unroll
;       for (int r = 0; r < 4; ++r) { float v = sc[qi][kt][r] * sl2;
;         if (masked) { int kp = key0 + kt * 16 + fq * 4 + r; int dq = qw0 + qi * 16 + fr - kp; if (dq > 128 || dq < -128) v = -1e30f; }
;         sc[qi][kt][r] = v; mx = fmaxf(mx, v); }
;     mx = max_x16_x32(mx);
;     const float mnew = fmaxf(mrun[qi], mx);
;     const float alpha = __builtin_amdgcn_exp2f(mrun[qi] - mnew);
;     mrun[qi] = mnew;
;     float ps = 0.f;
; #pragma unroll
;     for (int kt = 0; kt < 4; ++kt)
; #pragma unroll
;       for (int r = 0; r < 4; ++r) { float pvv = __builtin_amdgcn_exp2f(sc[qi][kt][r] - mnew); ps += pvv; sc[qi][kt][r] = pvv; }
;     pf[qi][0] = pack8(sc[qi][0][0], sc[qi][0][1], sc[qi][0][2], sc[qi][0][3], sc[qi][1][0], sc[qi][1][1], sc[qi][1][2], sc[qi][1][3]);
;     pf[qi][1] = pack8(sc[qi][2][0], sc[qi][2][1], sc[qi][2][2], sc[qi][2][3], sc[qi][3][0], sc[qi][3][1], sc[qi][3][2], sc[qi][3][3]);
;     lrun[qi] = lrun[qi] * alpha + ps;
; #pragma unroll
;     for (int dt = 0; dt < 4; ++dt) O[qi][dt] *= alpha;
;   }
.LBB0_622:
	ds_read_b128 v[78:81], v202 offset:13312
	ds_read_b128 v[90:93], v202 offset:13376
	ds_read_b128 v[222:225], v202 offset:13440
	ds_read_b128 v[226:229], v202 offset:16640
	ds_read_b128 v[98:101], v202 offset:16704
	ds_read_b128 v[230:233], v202 offset:16768
	ds_read_b128 v[234:237], v202 offset:19968
	ds_read_b128 v[102:105], v202 offset:20032
	ds_read_b128 v[238:241], v202 offset:20096
	ds_read_b128 v[242:245], v202 offset:23296
	ds_read_b128 v[158:161], v202 offset:23360
	ds_read_b128 v[246:249], v202 offset:23424
	s_mov_b32 s44, 0xf149f2ca
	s_mov_b32 s8, 0x3e16c740
	s_and_b64 vcc, exec, s[0:1]
	s_waitcnt lgkmcnt(11)
	v_mfma_f32_16x16x32_bf16 v[82:85], v[78:81], v[2:5], 0
	v_mfma_f32_16x16x32_bf16 v[78:81], v[78:81], v[18:21], 0
	s_waitcnt lgkmcnt(10)
	v_mfma_f32_16x16x32_bf16 v[82:85], v[90:93], v[6:9], v[82:85]
	v_mfma_f32_16x16x32_bf16 v[78:81], v[90:93], v[14:17], v[78:81]
	s_waitcnt lgkmcnt(9)
	v_mfma_f32_16x16x32_bf16 v[82:85], v[222:225], v[10:13], v[82:85]
	v_mfma_f32_16x16x32_bf16 v[90:93], v[222:225], v[22:25], v[78:81]
	s_waitcnt lgkmcnt(8)
	v_mfma_f32_16x16x32_bf16 v[94:97], v[226:229], v[2:5], 0
	v_mfma_f32_16x16x32_bf16 v[78:81], v[226:229], v[18:21], 0
	s_waitcnt lgkmcnt(7)
	v_mfma_f32_16x16x32_bf16 v[94:97], v[98:101], v[6:9], v[94:97]
	v_mfma_f32_16x16x32_bf16 v[78:81], v[98:101], v[14:17], v[78:81]
	s_waitcnt lgkmcnt(6)
	v_mfma_f32_16x16x32_bf16 v[166:169], v[230:233], v[10:13], v[94:97]
	v_mfma_f32_16x16x32_bf16 v[94:97], v[230:233], v[22:25], v[78:81]
	s_waitcnt lgkmcnt(5)
	v_mfma_f32_16x16x32_bf16 v[98:101], v[234:237], v[2:5], 0
	v_mfma_f32_16x16x32_bf16 v[78:81], v[234:237], v[18:21], 0
	s_waitcnt lgkmcnt(4)
	v_mfma_f32_16x16x32_bf16 v[98:101], v[102:105], v[6:9], v[98:101]
	v_mfma_f32_16x16x32_bf16 v[78:81], v[102:105], v[14:17], v[78:81]
	s_waitcnt lgkmcnt(3)
	v_mfma_f32_16x16x32_bf16 v[174:177], v[238:241], v[10:13], v[98:101]
	v_mfma_f32_16x16x32_bf16 v[98:101], v[238:241], v[22:25], v[78:81]
	s_waitcnt lgkmcnt(2)
	v_mfma_f32_16x16x32_bf16 v[102:105], v[242:245], v[2:5], 0
	v_mfma_f32_16x16x32_bf16 v[78:81], v[242:245], v[18:21], 0
	s_waitcnt lgkmcnt(1)
	v_mfma_f32_16x16x32_bf16 v[102:105], v[158:161], v[6:9], v[102:105]
	v_mfma_f32_16x16x32_bf16 v[78:81], v[158:161], v[14:17], v[78:81]
	s_waitcnt lgkmcnt(0)
	v_mfma_f32_16x16x32_bf16 v[188:191], v[246:249], v[10:13], v[102:105]
	v_mfma_f32_16x16x32_bf16 v[102:105], v[246:249], v[22:25], v[78:81]
	v_max3_f32 v159, v90, s44, v91
	s_nop 0
	s_nop 6
	v_max3_f32 v78, v82, s44, v83
	v_max3_f32 v78, v78, v84, v85
	v_max3_f32 v78, v78, v166, v167
	v_max3_f32 v78, v78, v168, v169
	v_max3_f32 v78, v78, v174, v175
	v_max3_f32 v78, v78, v176, v177
	v_max3_f32 v78, v78, v188, v189
	v_max3_f32 v78, v78, v190, v191
	v_mul_f32_e32 v78, 0x3e16c740, v78
	v_mov_b32_e32 v79, v78
	s_nop 1
	v_permlane32_swap_b32_e32 v78, v79
	v_max_f32_e32 v79, v79, v79
	v_max_f32_e32 v78, v78, v78
	v_max_f32_e32 v78, v78, v79
	v_mov_b32_e32 v79, v78
	s_nop 1
	v_permlane16_swap_b32_e32 v78, v79
	v_max3_f32 v218, v156, v78, v79
	v_max3_f32 v159, v159, v92, v93
	v_fma_f32 v79, v82, s8, -v218
	v_max3_f32 v159, v159, v94, v95
	v_sub_f32_e32 v78, v156, v218
	v_exp_f32_e32 v156, v79
	v_fma_f32 v79, v83, s8, -v218
	v_max3_f32 v159, v159, v96, v97
	v_exp_f32_e32 v160, v79
	v_fma_f32 v79, v84, s8, -v218
	v_max3_f32 v159, v159, v98, v99
	v_exp_f32_e32 v158, v79
	v_fma_f32 v79, v85, s8, -v218
	v_max3_f32 v159, v159, v100, v101
	v_exp_f32_e32 v162, v79
	v_fma_f32 v79, v166, s8, -v218
	v_max3_f32 v159, v159, v102, v103
	v_exp_f32_e32 v166, v79
	v_fma_f32 v79, v167, s8, -v218
	v_max3_f32 v159, v159, v104, v105
	v_exp_f32_e32 v164, v79
	v_fma_f32 v79, v168, s8, -v218
	v_mul_f32_e32 v159, 0x3e16c740, v159
	v_mov_b32_e32 v161, v159
	v_exp_f32_e32 v168, v79
	v_fma_f32 v79, v169, s8, -v218
	v_permlane32_swap_b32_e32 v159, v161
	v_exp_f32_e32 v172, v79
	v_fma_f32 v79, v174, s8, -v218
	v_max_f32_e32 v161, v161, v161
	v_max_f32_e32 v159, v159, v159
	v_exp_f32_e32 v170, v79
	v_fma_f32 v79, v175, s8, -v218
	v_max_f32_e32 v159, v159, v161
	v_exp_f32_e32 v174, v79
	v_fma_f32 v79, v176, s8, -v218
	v_exp_f32_e32 v176, v78
	v_mov_b32_e32 v161, v159
	s_nop 1
	v_permlane16_swap_b32_e32 v159, v161
	v_max3_f32 v219, v157, v159, v161
	v_fma_f32 v90, v90, s8, -v219
	v_exp_f32_e32 v186, v79
	v_fma_f32 v79, v177, s8, -v218
	v_pk_mul_f32 v[68:69], v[68:69], v[176:177] op_sel_hi:[1,0]
	v_pk_mul_f32 v[66:67], v[66:67], v[176:177] op_sel_hi:[1,0]
	v_pk_mul_f32 v[72:73], v[72:73], v[176:177] op_sel_hi:[1,0]
	v_pk_mul_f32 v[70:71], v[70:71], v[176:177] op_sel_hi:[1,0]
	v_pk_mul_f32 v[76:77], v[76:77], v[176:177] op_sel_hi:[1,0]
	v_pk_mul_f32 v[74:75], v[74:75], v[176:177] op_sel_hi:[1,0]
	v_pk_mul_f32 v[88:89], v[88:89], v[176:177] op_sel_hi:[1,0]
	v_pk_mul_f32 v[86:87], v[86:87], v[176:177] op_sel_hi:[1,0]
	v_sub_f32_e32 v177, v157, v219
	v_exp_f32_e32 v157, v90
	v_fma_f32 v90, v91, s8, -v219
	v_exp_f32_e32 v161, v90
	v_fma_f32 v90, v92, s8, -v219
	v_exp_f32_e32 v159, v90
	v_fma_f32 v90, v93, s8, -v219
	v_exp_f32_e32 v163, v90
	v_fma_f32 v90, v94, s8, -v219
	v_exp_f32_e32 v167, v90
	v_fma_f32 v90, v95, s8, -v219
	v_exp_f32_e32 v165, v90
	v_fma_f32 v90, v96, s8, -v219
	v_exp_f32_e32 v169, v90
	v_fma_f32 v90, v97, s8, -v219
	v_exp_f32_e32 v173, v90
	v_fma_f32 v90, v98, s8, -v219
	v_exp_f32_e32 v177, v177
	v_exp_f32_e32 v171, v90
	v_fma_f32 v90, v99, s8, -v219
	v_exp_f32_e32 v175, v90
	v_fma_f32 v90, v100, s8, -v219
	v_exp_f32_e32 v187, v90
	v_fma_f32 v90, v101, s8, -v219
	v_exp_f32_e32 v185, v90
	v_fma_f32 v90, v102, s8, -v219
	v_mov_b32_e32 v98, v177
	v_add_u32_e32 v102, 0x8800, v203
	v_pk_mul_f32 v[52:53], v[52:53], v[98:99] op_sel_hi:[1,0]
	v_pk_mul_f32 v[50:51], v[50:51], v[98:99] op_sel_hi:[1,0]
	v_pk_mul_f32 v[56:57], v[56:57], v[98:99] op_sel_hi:[1,0]
	v_pk_mul_f32 v[54:55], v[54:55], v[98:99] op_sel_hi:[1,0]
	v_pk_mul_f32 v[60:61], v[60:61], v[98:99] op_sel_hi:[1,0]
	v_pk_mul_f32 v[58:59], v[58:59], v[98:99] op_sel_hi:[1,0]
	v_pk_mul_f32 v[64:65], v[64:65], v[98:99] op_sel_hi:[1,0]
	v_pk_mul_f32 v[62:63], v[62:63], v[98:99] op_sel_hi:[1,0]
	ds_read2_b64 v[98:101], v102 offset0:128 offset1:132
	v_cvt_pk_bf16_f32 v82, v156, v160
	v_cvt_pk_bf16_f32 v83, v158, v162
	v_cvt_pk_bf16_f32 v84, v166, v164
	v_cvt_pk_bf16_f32 v85, v168, v172
	v_cvt_pk_bf16_f32 v94, v157, v161
	v_cvt_pk_bf16_f32 v95, v159, v163
	v_cvt_pk_bf16_f32 v96, v167, v165
	v_cvt_pk_bf16_f32 v97, v169, v173
	v_exp_f32_e32 v184, v79
	v_fma_f32 v79, v188, s8, -v218
	s_waitcnt lgkmcnt(0)
; DEV f32x4 mfma16(bf16x8 a, bf16x8 b, f32x4 c) { return __builtin_amdgcn_mfma_f32_16x16x32_bf16(a, b, c, 0, 0, 0); }
; template <int KS>
; DEV void attn_chunk(const unsigned char* Kl, const unsigned char* Vl, const bf16x8 (&qf)[2][KS], f32x4 (&O)[2][4], float (&mrun)[2], float (&lrun)[2],
;                     bool masked, int key0, int qw0, float sl2, int lane, int fr, int fq) {
;     ...
; #pragma unroll
;   for (int dt = 0; dt < 4; ++dt)
; #pragma unroll
;     for (int sub = 0; sub < 2; ++sub) {
;       const unsigned char* vp = Vl + ((dt * 16 + fr) * VP + sub * 32 + fq * 4) * 2;
;       u32x2 v0 = *reinterpret_cast<const u32x2*>(vp), v1 = *reinterpret_cast<const u32x2*>(vp + 32);
;       u32x4 vv = {v0[0], v0[1], v1[0], v1[1]};
;       bf16x8 vf = *reinterpret_cast<bf16x8*>(&vv);
;       O[0][dt] = mfma16(vf, pf[0][sub], O[0][dt]); O[1][dt] = mfma16(vf, pf[1][sub], O[1][dt]);
;     }
	v_mfma_f32_16x16x32_bf16 v[66:69], v[98:101], v[82:85], v[66:69]
	v_exp_f32_e32 v194, v79
	v_fma_f32 v79, v189, s8, -v218
	v_exp_f32_e32 v195, v90
	v_mfma_f32_16x16x32_bf16 v[50:53], v[98:101], v[94:97], v[50:53]
	ds_read2_b64 v[98:101], v102 offset0:136 offset1:140
	v_fma_f32 v90, v103, s8, -v219
	v_exp_f32_e32 v192, v79
	v_fma_f32 v79, v190, s8, -v218
	v_exp_f32_e32 v193, v90
	v_fma_f32 v90, v104, s8, -v219
	v_exp_f32_e32 v190, v79
	v_fma_f32 v79, v191, s8, -v218
	v_exp_f32_e32 v191, v90
	v_fma_f32 v90, v105, s8, -v219
	v_exp_f32_e32 v188, v79
	v_exp_f32_e32 v189, v90
	v_cvt_pk_bf16_f32 v78, v170, v174
	v_cvt_pk_bf16_f32 v79, v186, v184
	v_cvt_pk_bf16_f32 v80, v194, v192
	v_cvt_pk_bf16_f32 v81, v190, v188
	v_cvt_pk_bf16_f32 v90, v171, v175
	v_cvt_pk_bf16_f32 v91, v187, v185
	v_cvt_pk_bf16_f32 v92, v195, v193
	v_cvt_pk_bf16_f32 v93, v191, v189
	v_add_u32_e32 v102, 0x9000, v203
	s_waitcnt lgkmcnt(0)
	v_mfma_f32_16x16x32_bf16 v[66:69], v[98:101], v[78:81], v[66:69]
	v_mfma_f32_16x16x32_bf16 v[50:53], v[98:101], v[90:93], v[50:53]
	ds_read2_b64 v[98:101], v102 offset0:160 offset1:164
	s_waitcnt lgkmcnt(0)
	v_mfma_f32_16x16x32_bf16 v[70:73], v[98:101], v[82:85], v[70:73]
	v_mfma_f32_16x16x32_bf16 v[54:57], v[98:101], v[94:97], v[54:57]
	ds_read2_b64 v[98:101], v102 offset0:168 offset1:172
	v_add_u32_e32 v102, 0x9800, v203
	s_waitcnt lgkmcnt(0)
	v_mfma_f32_16x16x32_bf16 v[70:73], v[98:101], v[78:81], v[70:73]
	v_mfma_f32_16x16x32_bf16 v[54:57], v[98:101], v[90:93], v[54:57]
	ds_read2_b64 v[98:101], v102 offset0:192 offset1:196
	s_waitcnt lgkmcnt(0)
	v_mfma_f32_16x16x32_bf16 v[74:77], v[98:101], v[82:85], v[74:77]
	v_mfma_f32_16x16x32_bf16 v[58:61], v[98:101], v[94:97], v[58:61]
	ds_read2_b64 v[98:101], v102 offset0:200 offset1:204
	v_add_u32_e32 v102, 0xa000, v203
	s_waitcnt lgkmcnt(0)
	v_mfma_f32_16x16x32_bf16 v[74:77], v[98:101], v[78:81], v[74:77]
	v_mfma_f32_16x16x32_bf16 v[58:61], v[98:101], v[90:93], v[58:61]
	ds_read2_b64 v[98:101], v102 offset0:224 offset1:228
	s_waitcnt lgkmcnt(0)
	v_mfma_f32_16x16x32_bf16 v[82:85], v[98:101], v[82:85], v[86:89]
	s_nop 2
	ds_read2_b64 v[86:89], v102 offset0:232 offset1:236
	v_mfma_f32_16x16x32_bf16 v[62:65], v[98:101], v[94:97], v[62:65]
	s_waitcnt lgkmcnt(0)
	v_mfma_f32_16x16x32_bf16 v[78:81], v[86:89], v[78:81], v[82:85]
	v_mfma_f32_16x16x32_bf16 v[62:65], v[86:89], v[90:93], v[62:65]
	s_cbranch_vccnz .LBB0_611
	ds_write_b128 v199, v[26:29]
	s_and_saveexec_b64 s[0:1], s[40:41]
	s_cbranch_execz .LBB0_610
	ds_write_b128 v200, v[30:33]
	s_branch .LBB0_610
